# w_in GEMM epilogue: 8 row-scale loads hoisted, 15 serializing vmcnt(0) waits between store groups removed
# speedup vs baseline: 1.0031x; 1.0005x over previous
; __device__ __forceinline__ unsigned cvt_pk_bf16(float lo, float hi) { unsigned r; asm volatile("v_cvt_pk_bf16_f32 %0, %1, %2" : "=v"(r) : "v"(lo), "v"(hi)); return r; }
;     __device__ __forceinline__ void operator()(const f32x4 (&acc)[2][2][4][2], const Unit& u, int wr, int wc, int fr, int fq) const {
;         const int row0 = u.pm * BM + wr * 64 + fr;
; #pragma unroll
;         for (int bj = 0; bj < 2; ++bj) {
;             const int c = u.pn * BM + bj * HALF + wc * 32 + 8 * fq;
;             bf16_t* base; size_t ld;
;             if (MODE == 1) { if (c < 1024) { base = O + c; ld = 1024; } else { base = O2 + (c - 1024); ld = 1536; } }
;             else if (MODE == 2) { base = O + (c >> 6) * 96 + (c & 63); ld = (size_t)ldc; }
;             else { base = O + c; ld = (size_t)ldc; }
; #pragma unroll
;             for (int ai = 0; ai < 2; ++ai)
; #pragma unroll
;                 for (int m = 0; m < 4; ++m) {
;                     const float rsc = rs ? rs[row0 + ai * HALF + m * 16] : 1.0f;
;                     const f32x4 v0 = acc[ai][bj][m][0] * rsc, v1 = acc[ai][bj][m][1] * rsc;
;                     u32x4 w; w.x = cvt_pk_bf16(v0[0], v0[1]); w.y = cvt_pk_bf16(v0[2], v0[3]); w.z = cvt_pk_bf16(v1[0], v1[1]); w.w = cvt_pk_bf16(v1[2], v1[3]);
;                     *(u32x4*)(base + (size_t)(row0 + ai * HALF + m * 16) * ld) = w;
;                 }
;         }
.LBB0_528:
	v_lshl_add_u32 v144, s2, 8, v153
	v_ashrrev_i32_e32 v145, 31, v144
	v_cndmask_b32_e64 v146, 0, 1, s[12:13]
	v_mov_b32_e32 v152, 1.0
	v_cmp_ne_u32_e64 s[2:3], 1, v146
	s_andn2_b64 vcc, exec, s[12:13]
	v_lshl_add_u64 v[146:147], v[144:145], 2, s[4:5]
	global_load_dword v166, v[146:147], off
	global_load_dword v168, v[146:147], off offset:64
	global_load_dword v170, v[146:147], off offset:128
	global_load_dword v172, v[146:147], off offset:192
	global_load_dword v174, v[146:147], off offset:512
	global_load_dword v176, v[146:147], off offset:576
	global_load_dword v178, v[146:147], off offset:640
	global_load_dword v180, v[146:147], off offset:704
	v_mov_b32_e32 v154, 1.0
	s_cbranch_vccnz .LBB0_530
.LBB0_530:
	v_lshl_or_b32 v148, s28, 8, v156
	v_readlane_b32 s30, v253, 47
	v_ashrrev_i32_e32 v149, 31, v148
	v_readlane_b32 s31, v253, 48
	v_cmp_gt_i32_e32 vcc, s49, v148
	s_waitcnt vmcnt(0)
	v_pk_mul_f32 v[124:125], v[124:125], v[166:167] op_sel_hi:[1,0]
	v_lshl_add_u64 v[150:151], v[148:149], 1, s[30:31]
	v_readlane_b32 s30, v253, 51
	v_mov_b32_e32 v149, v131
	v_readlane_b32 s31, v253, 52
	v_cndmask_b32_e32 v145, v160, v161, vcc
	v_pk_mul_f32 v[126:127], v[126:127], v[166:167] op_sel_hi:[1,0]
	v_lshl_add_u64 v[162:163], v[148:149], 1, s[30:31]
	v_lshl_add_u64 v[162:163], v[162:163], 0, s[18:19]
	v_cndmask_b32_e32 v151, v163, v151, vcc
	v_cndmask_b32_e32 v150, v162, v150, vcc
	v_pk_mul_f32 v[162:163], v[122:123], v[166:167] op_sel_hi:[1,0]
	v_pk_mul_f32 v[122:123], v[120:121], v[166:167] op_sel_hi:[1,0]
	v_cvt_pk_bf16_f32 v120, v124, v125
	v_mad_i64_i32 v[124:125], s[30:31], v145, v144, 0
	v_lshl_add_u64 v[124:125], v[124:125], 1, v[150:151]
	v_cvt_pk_bf16_f32 v121, v126, v127
	v_cvt_pk_bf16_f32 v122, v122, v123
	v_cvt_pk_bf16_f32 v123, v162, v163
	global_store_dwordx4 v[124:125], v[120:123], off
	s_and_b64 vcc, exec, s[2:3]
	s_nop 0
	v_or_b32_e32 v120, 16, v144
	v_ashrrev_i32_e32 v121, 31, v120
	v_lshl_add_u64 v[122:123], v[120:121], 2, s[4:5]
	s_cbranch_vccnz .LBB0_532
.LBB0_532:
	s_nop 1
	v_pk_mul_f32 v[116:117], v[116:117], v[168:169] op_sel_hi:[1,0]
	v_pk_mul_f32 v[124:125], v[114:115], v[168:169] op_sel_hi:[1,0]
	v_pk_mul_f32 v[114:115], v[112:113], v[168:169] op_sel_hi:[1,0]
	v_cvt_pk_bf16_f32 v112, v116, v117
	v_mad_i64_i32 v[116:117], s[30:31], v145, v120, 0
	v_lshl_add_u64 v[116:117], v[116:117], 1, v[150:151]
	v_pk_mul_f32 v[118:119], v[118:119], v[168:169] op_sel_hi:[1,0]
	s_and_b64 vcc, exec, s[2:3]
	v_cvt_pk_bf16_f32 v113, v118, v119
	v_cvt_pk_bf16_f32 v114, v114, v115
	v_cvt_pk_bf16_f32 v115, v124, v125
	global_store_dwordx4 v[116:117], v[112:115], off
	v_mov_b32_e32 v116, 1.0
	v_mov_b32_e32 v118, 1.0
	v_or_b32_e32 v112, 32, v144
	v_ashrrev_i32_e32 v113, 31, v112
	v_lshl_add_u64 v[114:115], v[112:113], 2, s[4:5]
	s_cbranch_vccnz .LBB0_534
.LBB0_534:
	s_nop 1
	v_pk_mul_f32 v[108:109], v[108:109], v[170:171] op_sel_hi:[1,0]
	v_pk_mul_f32 v[124:125], v[106:107], v[170:171] op_sel_hi:[1,0]
	v_pk_mul_f32 v[106:107], v[104:105], v[170:171] op_sel_hi:[1,0]
	v_cvt_pk_bf16_f32 v104, v108, v109
	v_mad_i64_i32 v[108:109], s[30:31], v145, v112, 0
	v_lshl_add_u64 v[108:109], v[108:109], 1, v[150:151]
	v_pk_mul_f32 v[110:111], v[110:111], v[170:171] op_sel_hi:[1,0]
	s_and_b64 vcc, exec, s[2:3]
	v_cvt_pk_bf16_f32 v105, v110, v111
	v_cvt_pk_bf16_f32 v106, v106, v107
	v_cvt_pk_bf16_f32 v107, v124, v125
	global_store_dwordx4 v[108:109], v[104:107], off
	s_nop 1
	v_or_b32_e32 v104, 48, v144
	v_ashrrev_i32_e32 v105, 31, v104
	v_lshl_add_u64 v[106:107], v[104:105], 2, s[4:5]
	s_cbranch_vccnz .LBB0_536
.LBB0_536:
	s_nop 1
	v_pk_mul_f32 v[100:101], v[100:101], v[172:173] op_sel_hi:[1,0]
	v_pk_mul_f32 v[108:109], v[98:99], v[172:173] op_sel_hi:[1,0]
	v_pk_mul_f32 v[98:99], v[96:97], v[172:173] op_sel_hi:[1,0]
	v_cvt_pk_bf16_f32 v96, v100, v101
	v_mad_i64_i32 v[100:101], s[30:31], v145, v104, 0
	v_lshl_add_u64 v[100:101], v[100:101], 1, v[150:151]
	v_pk_mul_f32 v[102:103], v[102:103], v[172:173] op_sel_hi:[1,0]
	s_and_b64 vcc, exec, s[2:3]
	v_cvt_pk_bf16_f32 v97, v102, v103
	v_cvt_pk_bf16_f32 v98, v98, v99
	v_cvt_pk_bf16_f32 v99, v108, v109
	global_store_dwordx4 v[100:101], v[96:99], off
	v_mov_b32_e32 v100, 1.0
	v_mov_b32_e32 v102, 1.0
	v_add_u32_e32 v96, 0x80, v144
	v_ashrrev_i32_e32 v97, 31, v96
	v_lshl_add_u64 v[98:99], v[96:97], 2, s[4:5]
	s_cbranch_vccnz .LBB0_538
.LBB0_538:
	s_nop 1
	v_pk_mul_f32 v[92:93], v[92:93], v[174:175] op_sel_hi:[1,0]
	v_pk_mul_f32 v[108:109], v[90:91], v[174:175] op_sel_hi:[1,0]
	v_pk_mul_f32 v[90:91], v[88:89], v[174:175] op_sel_hi:[1,0]
	v_cvt_pk_bf16_f32 v88, v92, v93
	v_mad_i64_i32 v[92:93], s[30:31], v145, v96, 0
	v_lshl_add_u64 v[92:93], v[92:93], 1, v[150:151]
	v_pk_mul_f32 v[94:95], v[94:95], v[174:175] op_sel_hi:[1,0]
	s_and_b64 vcc, exec, s[2:3]
	v_cvt_pk_bf16_f32 v89, v94, v95
	v_cvt_pk_bf16_f32 v90, v90, v91
	v_cvt_pk_bf16_f32 v91, v108, v109
	global_store_dwordx4 v[92:93], v[88:91], off
	s_nop 1
	v_add_u32_e32 v88, 0x90, v144
	v_ashrrev_i32_e32 v89, 31, v88
	v_lshl_add_u64 v[90:91], v[88:89], 2, s[4:5]
	s_cbranch_vccnz .LBB0_540
.LBB0_540:
	s_nop 1
	v_pk_mul_f32 v[84:85], v[84:85], v[176:177] op_sel_hi:[1,0]
	v_pk_mul_f32 v[92:93], v[82:83], v[176:177] op_sel_hi:[1,0]
	v_pk_mul_f32 v[82:83], v[80:81], v[176:177] op_sel_hi:[1,0]
	v_cvt_pk_bf16_f32 v80, v84, v85
	v_mad_i64_i32 v[84:85], s[30:31], v145, v88, 0
	v_lshl_add_u64 v[84:85], v[84:85], 1, v[150:151]
	v_pk_mul_f32 v[86:87], v[86:87], v[176:177] op_sel_hi:[1,0]
	s_and_b64 vcc, exec, s[2:3]
	v_cvt_pk_bf16_f32 v81, v86, v87
	v_cvt_pk_bf16_f32 v82, v82, v83
	v_cvt_pk_bf16_f32 v83, v92, v93
	global_store_dwordx4 v[84:85], v[80:83], off
	v_mov_b32_e32 v84, 1.0
	v_mov_b32_e32 v86, 1.0
	v_add_u32_e32 v80, 0xa0, v144
	v_ashrrev_i32_e32 v81, 31, v80
	v_lshl_add_u64 v[82:83], v[80:81], 2, s[4:5]
	s_cbranch_vccnz .LBB0_542
; __device__ __forceinline__ unsigned cvt_pk_bf16(float lo, float hi) { unsigned r; asm volatile("v_cvt_pk_bf16_f32 %0, %1, %2" : "=v"(r) : "v"(lo), "v"(hi)); return r; }
;     __device__ __forceinline__ void operator()(const f32x4 (&acc)[2][2][4][2], const Unit& u, int wr, int wc, int fr, int fq) const {
;         const int row0 = u.pm * BM + wr * 64 + fr;
; #pragma unroll
;         for (int bj = 0; bj < 2; ++bj) {
;             const int c = u.pn * BM + bj * HALF + wc * 32 + 8 * fq;
;             bf16_t* base; size_t ld;
;             if (MODE == 1) { if (c < 1024) { base = O + c; ld = 1024; } else { base = O2 + (c - 1024); ld = 1536; } }
;             else if (MODE == 2) { base = O + (c >> 6) * 96 + (c & 63); ld = (size_t)ldc; }
;             else { base = O + c; ld = (size_t)ldc; }
; #pragma unroll
;             for (int ai = 0; ai < 2; ++ai)
; #pragma unroll
;                 for (int m = 0; m < 4; ++m) {
;                     const float rsc = rs ? rs[row0 + ai * HALF + m * 16] : 1.0f;
;                     const f32x4 v0 = acc[ai][bj][m][0] * rsc, v1 = acc[ai][bj][m][1] * rsc;
;                     u32x4 w; w.x = cvt_pk_bf16(v0[0], v0[1]); w.y = cvt_pk_bf16(v0[2], v0[3]); w.z = cvt_pk_bf16(v1[0], v1[1]); w.w = cvt_pk_bf16(v1[2], v1[3]);
;                     *(u32x4*)(base + (size_t)(row0 + ai * HALF + m * 16) * ld) = w;
;                 }
;         }
.LBB0_542:
	s_nop 1
	v_pk_mul_f32 v[76:77], v[76:77], v[178:179] op_sel_hi:[1,0]
	v_pk_mul_f32 v[92:93], v[74:75], v[178:179] op_sel_hi:[1,0]
	v_pk_mul_f32 v[74:75], v[72:73], v[178:179] op_sel_hi:[1,0]
	v_cvt_pk_bf16_f32 v72, v76, v77
	v_mad_i64_i32 v[76:77], s[30:31], v145, v80, 0
	v_lshl_add_u64 v[76:77], v[76:77], 1, v[150:151]
	v_pk_mul_f32 v[78:79], v[78:79], v[178:179] op_sel_hi:[1,0]
	s_and_b64 vcc, exec, s[2:3]
	v_cvt_pk_bf16_f32 v73, v78, v79
	v_cvt_pk_bf16_f32 v74, v74, v75
	v_cvt_pk_bf16_f32 v75, v92, v93
	global_store_dwordx4 v[76:77], v[72:75], off
	s_nop 1
	v_add_u32_e32 v72, 0xb0, v144
	v_ashrrev_i32_e32 v73, 31, v72
	v_lshl_add_u64 v[74:75], v[72:73], 2, s[4:5]
	s_cbranch_vccnz .LBB0_544
.LBB0_544:
	s_nop 1
	v_pk_mul_f32 v[68:69], v[68:69], v[180:181] op_sel_hi:[1,0]
	v_pk_mul_f32 v[76:77], v[62:63], v[180:181] op_sel_hi:[1,0]
	v_pk_mul_f32 v[62:63], v[60:61], v[180:181] op_sel_hi:[1,0]
	v_cvt_pk_bf16_f32 v60, v68, v69
	v_mad_i64_i32 v[68:69], s[30:31], v145, v72, 0
	v_pk_mul_f32 v[70:71], v[70:71], v[180:181] op_sel_hi:[1,0]
	v_lshl_add_u64 v[68:69], v[68:69], 1, v[150:151]
	v_cvt_pk_bf16_f32 v61, v70, v71
	v_cvt_pk_bf16_f32 v62, v62, v63
	v_cvt_pk_bf16_f32 v63, v76, v77
	global_store_dwordx4 v[68:69], v[60:63], off
	s_and_b64 vcc, exec, s[2:3]
	v_mov_b32_e32 v68, 1.0
	v_mov_b32_e32 v62, 1.0
	s_cbranch_vccnz .LBB0_546
.LBB0_546:
	v_or_b32_e32 v60, 0x80, v148
	v_readlane_b32 s30, v253, 47
	v_ashrrev_i32_e32 v61, 31, v60
	v_readlane_b32 s31, v253, 48
	v_cmp_gt_i32_e32 vcc, s49, v60
	s_nop 1
	v_pk_mul_f32 v[64:65], v[64:65], v[166:167] op_sel_hi:[1,0]
	v_lshl_add_u64 v[70:71], v[60:61], 1, s[30:31]
	v_readlane_b32 s30, v253, 51
	v_mov_b32_e32 v61, v131
	v_readlane_b32 s31, v253, 52
	v_cndmask_b32_e32 v63, v160, v161, vcc
	v_pk_mul_f32 v[66:67], v[66:67], v[166:167] op_sel_hi:[1,0]
	v_lshl_add_u64 v[76:77], v[60:61], 1, s[30:31]
	v_lshl_add_u64 v[76:77], v[76:77], 0, s[18:19]
	v_cndmask_b32_e32 v61, v77, v71, vcc
	v_cndmask_b32_e32 v60, v76, v70, vcc
	v_pk_mul_f32 v[70:71], v[58:59], v[166:167] op_sel_hi:[1,0]
	v_pk_mul_f32 v[58:59], v[56:57], v[166:167] op_sel_hi:[1,0]
	v_cvt_pk_bf16_f32 v56, v64, v65
	v_mad_i64_i32 v[64:65], s[30:31], v63, v144, 0
	v_lshl_add_u64 v[64:65], v[64:65], 1, v[60:61]
	s_and_b64 vcc, exec, s[2:3]
	v_cvt_pk_bf16_f32 v57, v66, v67
	v_cvt_pk_bf16_f32 v58, v58, v59
	v_cvt_pk_bf16_f32 v59, v70, v71
	global_store_dwordx4 v[64:65], v[56:59], off
	s_cbranch_vccnz .LBB0_548
.LBB0_548:
	s_nop 1
	v_pk_mul_f32 v[52:53], v[52:53], v[168:169] op_sel_hi:[1,0]
	v_pk_mul_f32 v[56:57], v[50:51], v[168:169] op_sel_hi:[1,0]
	v_pk_mul_f32 v[50:51], v[48:49], v[168:169] op_sel_hi:[1,0]
	v_cvt_pk_bf16_f32 v48, v52, v53
	v_mad_i64_i32 v[52:53], s[30:31], v63, v120, 0
	v_pk_mul_f32 v[54:55], v[54:55], v[168:169] op_sel_hi:[1,0]
	v_lshl_add_u64 v[52:53], v[52:53], 1, v[60:61]
	v_cvt_pk_bf16_f32 v49, v54, v55
	v_cvt_pk_bf16_f32 v50, v50, v51
	v_cvt_pk_bf16_f32 v51, v56, v57
	global_store_dwordx4 v[52:53], v[48:51], off
	s_and_b64 vcc, exec, s[2:3]
	s_nop 0
	v_mov_b32_e32 v48, 1.0
	v_mov_b32_e32 v50, 1.0
	s_cbranch_vccnz .LBB0_550
.LBB0_550:
	s_nop 1
	v_pk_mul_f32 v[44:45], v[44:45], v[170:171] op_sel_hi:[1,0]
	v_pk_mul_f32 v[52:53], v[42:43], v[170:171] op_sel_hi:[1,0]
	v_pk_mul_f32 v[42:43], v[40:41], v[170:171] op_sel_hi:[1,0]
	v_cvt_pk_bf16_f32 v40, v44, v45
	v_mad_i64_i32 v[44:45], s[30:31], v63, v112, 0
	v_lshl_add_u64 v[44:45], v[44:45], 1, v[60:61]
	s_and_b64 vcc, exec, s[2:3]
	v_pk_mul_f32 v[46:47], v[46:47], v[170:171] op_sel_hi:[1,0]
	s_nop 0
	v_cvt_pk_bf16_f32 v41, v46, v47
	v_cvt_pk_bf16_f32 v42, v42, v43
	v_cvt_pk_bf16_f32 v43, v52, v53
	global_store_dwordx4 v[44:45], v[40:43], off
	s_cbranch_vccnz .LBB0_552
.LBB0_552:
	s_nop 1
	v_pk_mul_f32 v[36:37], v[36:37], v[172:173] op_sel_hi:[1,0]
	v_pk_mul_f32 v[40:41], v[34:35], v[172:173] op_sel_hi:[1,0]
	v_pk_mul_f32 v[34:35], v[32:33], v[172:173] op_sel_hi:[1,0]
	v_cvt_pk_bf16_f32 v32, v36, v37
	v_mad_i64_i32 v[36:37], s[30:31], v63, v104, 0
	v_pk_mul_f32 v[38:39], v[38:39], v[172:173] op_sel_hi:[1,0]
	v_lshl_add_u64 v[36:37], v[36:37], 1, v[60:61]
	v_cvt_pk_bf16_f32 v33, v38, v39
	v_cvt_pk_bf16_f32 v34, v34, v35
	v_cvt_pk_bf16_f32 v35, v40, v41
	global_store_dwordx4 v[36:37], v[32:35], off
	s_and_b64 vcc, exec, s[2:3]
	s_nop 0
	v_mov_b32_e32 v32, 1.0
	v_mov_b32_e32 v34, 1.0
	s_cbranch_vccnz .LBB0_554
.LBB0_554:
	s_nop 1
	v_pk_mul_f32 v[28:29], v[28:29], v[174:175] op_sel_hi:[1,0]
	v_pk_mul_f32 v[36:37], v[26:27], v[174:175] op_sel_hi:[1,0]
	v_pk_mul_f32 v[26:27], v[24:25], v[174:175] op_sel_hi:[1,0]
	v_cvt_pk_bf16_f32 v24, v28, v29
	v_mad_i64_i32 v[28:29], s[30:31], v63, v96, 0
	v_lshl_add_u64 v[28:29], v[28:29], 1, v[60:61]
	s_and_b64 vcc, exec, s[2:3]
	v_pk_mul_f32 v[30:31], v[30:31], v[174:175] op_sel_hi:[1,0]
	s_nop 0
	v_cvt_pk_bf16_f32 v25, v30, v31
	v_cvt_pk_bf16_f32 v26, v26, v27
	v_cvt_pk_bf16_f32 v27, v36, v37
	global_store_dwordx4 v[28:29], v[24:27], off
	s_cbranch_vccnz .LBB0_556
.LBB0_556:
	s_nop 1
	v_pk_mul_f32 v[20:21], v[20:21], v[176:177] op_sel_hi:[1,0]
	v_pk_mul_f32 v[24:25], v[18:19], v[176:177] op_sel_hi:[1,0]
	v_pk_mul_f32 v[18:19], v[16:17], v[176:177] op_sel_hi:[1,0]
	v_cvt_pk_bf16_f32 v16, v20, v21
	v_mad_i64_i32 v[20:21], s[30:31], v63, v88, 0
	v_pk_mul_f32 v[22:23], v[22:23], v[176:177] op_sel_hi:[1,0]
	v_lshl_add_u64 v[20:21], v[20:21], 1, v[60:61]
	v_cvt_pk_bf16_f32 v17, v22, v23
	v_cvt_pk_bf16_f32 v18, v18, v19
	v_cvt_pk_bf16_f32 v19, v24, v25
	global_store_dwordx4 v[20:21], v[16:19], off
	s_and_b64 vcc, exec, s[2:3]
	s_nop 0
	v_mov_b32_e32 v16, 1.0
	v_mov_b32_e32 v18, 1.0
	s_cbranch_vccnz .LBB0_558
.LBB0_558:
	s_nop 1
	v_pk_mul_f32 v[12:13], v[12:13], v[178:179] op_sel_hi:[1,0]
	v_pk_mul_f32 v[20:21], v[10:11], v[178:179] op_sel_hi:[1,0]
	v_pk_mul_f32 v[10:11], v[8:9], v[178:179] op_sel_hi:[1,0]
	v_cvt_pk_bf16_f32 v8, v12, v13
	v_mad_i64_i32 v[12:13], s[30:31], v63, v80, 0
	v_lshl_add_u64 v[12:13], v[12:13], 1, v[60:61]
	s_and_b64 vcc, exec, s[2:3]
	v_pk_mul_f32 v[14:15], v[14:15], v[178:179] op_sel_hi:[1,0]
	s_nop 0
	v_cvt_pk_bf16_f32 v9, v14, v15
	v_cvt_pk_bf16_f32 v10, v10, v11
	v_cvt_pk_bf16_f32 v11, v20, v21
	global_store_dwordx4 v[12:13], v[8:11], off
	s_cbranch_vccnz .LBB0_560
.LBB0_560:
	s_nop 1
	v_pk_mul_f32 v[4:5], v[4:5], v[180:181] op_sel_hi:[1,0]
	v_pk_mul_f32 v[8:9], v[2:3], v[180:181] op_sel_hi:[1,0]
	v_pk_mul_f32 v[2:3], v[0:1], v[180:181] op_sel_hi:[1,0]
	v_cvt_pk_bf16_f32 v0, v4, v5
	v_mad_i64_i32 v[4:5], s[2:3], v63, v72, 0
	v_lshl_add_u64 v[4:5], v[4:5], 1, v[60:61]
	s_andn2_b64 vcc, exec, s[0:1]
	s_mov_b64 s[0:1], -1
	v_pk_mul_f32 v[6:7], v[6:7], v[180:181] op_sel_hi:[1,0]
	s_nop 0
	v_cvt_pk_bf16_f32 v1, v6, v7
	v_cvt_pk_bf16_f32 v2, v2, v3
	v_cvt_pk_bf16_f32 v3, v8, v9
	global_store_dwordx4 v[4:5], v[0:3], off
	s_cbranch_vccnz .LBB0_521
	s_andn2_b64 vcc, exec, s[10:11]
	s_cbranch_vccnz .LBB0_520
	s_barrier
	s_branch .LBB0_520
